# conversion loop: 8 LDS row reads issued together (store ladder de-serialised) + windows 8/8.75/8 items per idle WG
# baseline (speedup 1.0000x reference)
; __device__ __forceinline__ int row_map(int mode, int n) {
;     if (mode == 0) return n;
;     if (mode == 1) return (n >> 7) * 256 + (n & 127);
;     if (mode == 2) return (n >> 7) * 256 + 128 + (n & 127);
;     if (n < 1024 || n >= 3072) { const int c = n & 31; return (n & ~31) + 16 * ((c >> 2) & 1) + 4 * (c >> 3) + (c & 3); }
;     const int dd = (n - 1024) & 127; return (n - dd) + ((((dd >> 4) & 3) << 5) | ((dd >> 6) << 4) | (dd & 15));
; }
; __global__ void __launch_bounds__(NTHREADS, 2) mega_fwd(Args args) {
;     ...
;         for (int it = bid; it < DEPTH * I_LAYER; it += G, nbuf ^= 1) {
;             const int itr = DEPTH * I_LAYER - 1 - it;
;             const int l = itr / I_LAYER; int r = itr - l * I_LAYER;
;             unsigned char* WL = P_WL(l);
;             const float* W; int K, N, mode = 0; bf16* WT; const float* rg = nullptr;
;             if (r < 3 * I_GU) { const int w = r / I_GU; r -= w * I_GU;
;                 if (w < 2) { W = args.in[2 + w] + (size_t)l * D * FF; K = D; N = FF; WT = (bf16*)(WL + OFF_WGU1); rg = args.in[1] + (size_t)l * D; mode = 1 + w; }
;                 else { W = args.in[4] + (size_t)l * FF * D; K = FF; N = D; WT = (bf16*)(WL + OFF_WD1); } }
;             else if ((r -= 3 * I_GU) < 3 * I_GU) { const int w = r / I_GU; r -= w * I_GU;
;                 if (w < 2) { W = args.in[13 + w] + (size_t)l * D * FF; K = D; N = FF; WT = (bf16*)(WL + OFF_WGU2); rg = args.in[12] + (size_t)l * D; mode = 1 + w; }
;                 else { W = args.in[15] + (size_t)l * FF * D; K = FF; N = D; WT = (bf16*)(WL + OFF_WD2); } }
;             else if ((r -= 3 * I_GU) < I_IN) { W = args.in[6] + (size_t)l * D * INW; K = D; N = INW; WT = (bf16*)(WL + OFF_WIN); rg = args.in[5] + (size_t)l * D; mode = 3; }
;             else { r -= I_IN; W = args.in[11] + (size_t)l * D * D; K = D; N = D; WT = (bf16*)(WL + OFF_WOUT); }
;             tr_item_cu(W, K, N, WT, rg, mode, lds + nbuf * TC_BUF, r, wave, lane);
;         }
.Ldc_pre:
	v_ashrrev_i32_e32 v3, 5, v2
	v_lshl_add_u32 v77, s73, 4, v3
	v_add_u32_e32 v82, 2, v77
	v_lshrrev_b32_e32 v6, 2, v82
	v_and_b32_e32 v84, 16, v6
	v_lshlrev_b32_e32 v6, 2, v82
	v_and_b32_e32 v6, 16, v6
	v_lshrrev_b32_e32 v7, 1, v82
	v_add_u32_e32 v86, 4, v77
	v_and_or_b32 v85, v7, 12, v6
	v_lshrrev_b32_e32 v6, 2, v86
	v_and_b32_e32 v88, 16, v6
	v_lshlrev_b32_e32 v6, 2, v86
	v_and_b32_e32 v6, 16, v6
	v_lshrrev_b32_e32 v7, 1, v86
	v_add_u32_e32 v90, 6, v77
	v_and_or_b32 v89, v7, 12, v6
	v_lshrrev_b32_e32 v6, 2, v90
	v_and_b32_e32 v92, 16, v6
	v_lshlrev_b32_e32 v6, 2, v90
	v_and_b32_e32 v6, 16, v6
	v_lshrrev_b32_e32 v7, 1, v90
	v_add_u32_e32 v97, 10, v77
	v_and_or_b32 v93, v7, 12, v6
	v_lshrrev_b32_e32 v7, 2, v97
	s_add_u32 s36, s12, 0x900000
	v_and_b32_e32 v99, 16, v7
	v_lshlrev_b32_e32 v7, 2, v97
	s_addc_u32 s37, s13, 0
	s_load_dwordx2 s[12:13], s[0:1], 0x8
	s_load_dwordx4 s[4:7], s[0:1], 0x20
	s_load_dwordx4 s[8:11], s[0:1], 0x58
	s_load_dwordx2 s[14:15], s[0:1], 0x30
	s_load_dwordx2 s[16:17], s[0:1], 0x78
	v_and_b32_e32 v7, 16, v7
	v_lshrrev_b32_e32 v8, 1, v97
	v_add_u32_e32 v101, 12, v77
	v_and_or_b32 v100, v8, 12, v7
	v_lshrrev_b32_e32 v7, 2, v101
	v_and_b32_e32 v103, 16, v7
	v_lshlrev_b32_e32 v7, 2, v101
	v_and_b32_e32 v7, 16, v7
	v_lshrrev_b32_e32 v8, 1, v101
	v_add_u32_e32 v105, 14, v77
	s_lshl_b32 s18, s73, 5
	v_add_u32_e32 v94, 8, v77
	v_and_or_b32 v104, v8, 12, v7
	v_lshrrev_b32_e32 v7, 2, v105
	v_and_b32_e32 v4, 31, v2
	v_lshl_add_u32 v66, v3, 4, s18
	v_lshrrev_b32_e32 v5, 2, v77
	v_lshlrev_b32_e32 v3, 2, v3
	v_lshrrev_b32_e32 v6, 2, v94
	v_and_b32_e32 v107, 16, v7
	v_lshlrev_b32_e32 v7, 2, v105
	v_lshlrev_b32_e32 v2, 2, v4
	v_mov_b32_e32 v69, 0
	v_mul_u32_u24_e32 v76, 0x840, v4
	v_lshlrev_b32_e32 v78, 4, v4
	v_lshlrev_b32_e32 v4, 3, v4
	s_movk_i32 s18, 0x210
	v_and_b32_e32 v80, 0x7f, v77
	v_and_b32_e32 v81, 16, v5
	v_and_b32_e32 v3, 16, v3
	v_lshrrev_b32_e32 v5, 1, v77
	v_and_b32_e32 v83, 0x7f, v82
	v_and_b32_e32 v87, 0x7f, v86
	v_and_b32_e32 v91, 0x7f, v90
	v_and_b32_e32 v95, 0x7f, v94
	v_and_b32_e32 v96, 16, v6
	v_lshrrev_b32_e32 v6, 1, v94
	v_and_b32_e32 v98, 0x7f, v97
	v_and_b32_e32 v102, 0x7f, v101
	v_and_b32_e32 v106, 0x7f, v105
	v_and_b32_e32 v7, 16, v7
	v_lshrrev_b32_e32 v8, 1, v105
	v_ashrrev_i32_e32 v67, 31, v66
	v_lshlrev_b32_e32 v75, 1, v66
	v_mul_lo_u32 v79, v77, s18
	v_and_or_b32 v108, v8, 12, v7
	v_or_b32_e32 v109, 0x80, v80
	v_or_b32_e32 v110, 0x80, v83
	v_or_b32_e32 v111, 0x80, v87
	v_or_b32_e32 v112, 0x80, v91
	v_or_b32_e32 v113, 0x80, v95
	v_or_b32_e32 v114, 0x80, v98
	v_or_b32_e32 v115, 0x80, v102
	v_or_b32_e32 v116, 0x80, v106
	v_and_or_b32 v117, v5, 12, v3
	v_and_or_b32 v118, v6, 12, v3
	s_mov_b32 s19, 0
	s_sub_i32 s38, 0, s72
	s_sub_i32 s39, 0x137f, s72
	v_lshlrev_b32_e32 v70, 2, v2
	v_mov_b32_e32 v71, v69
	s_movk_i32 s40, 0xff00
	s_movk_i32 s41, 0xf7ff
	s_movk_i32 s42, 0xffe3
	v_lshlrev_b32_e32 v68, 1, v4
	s_mov_b32 s43, 0
	s_mov_b32 s44, s72
	s_cmp_lg_u32 s98, 0
	s_cbranch_scc1 .Ldc_ovr
	v_readlane_b32 s100, v254, 2
	s_movk_i32 s101, 0x137f
	s_nop 1
	s_mov_b32 s99, s100
	s_cmpk_lg_i32 s100, 0x100
	s_cbranch_scc1 .LBB0_33
	s_cmpk_lt_i32 s72, 0x80
	s_cbranch_scc1 .Ldc_lowhalf
	s_addk_i32 s44, 3520
	s_sub_i32 s38, 0, s44
	s_sub_i32 s39, 0x137f, s44
	s_branch .LBB0_33
.Ldc_lowhalf:
	s_addk_i32 s44, 2496
	s_sub_i32 s38, 0, s44
	s_sub_i32 s39, 0x137f, s44
	s_movk_i32 s100, 1280
	s_branch .LBB0_33

; __global__ void __launch_bounds__(NTHREADS, 2) mega_fwd(Args args) {
;     ...
;         for (int it = bid; it < DEPTH * I_LAYER; it += G, nbuf ^= 1) {
;             const int itr = DEPTH * I_LAYER - 1 - it;
;             const int l = itr / I_LAYER; int r = itr - l * I_LAYER;
;             unsigned char* WL = P_WL(l);
;             const float* W; int K, N, mode = 0; bf16* WT; const float* rg = nullptr;
;             if (r < 3 * I_GU) { const int w = r / I_GU; r -= w * I_GU;
;                 if (w < 2) { W = args.in[2 + w] + (size_t)l * D * FF; K = D; N = FF; WT = (bf16*)(WL + OFF_WGU1); rg = args.in[1] + (size_t)l * D; mode = 1 + w; }
;                 else { W = args.in[4] + (size_t)l * FF * D; K = FF; N = D; WT = (bf16*)(WL + OFF_WD1); } }
;             else if ((r -= 3 * I_GU) < 3 * I_GU) { const int w = r / I_GU; r -= w * I_GU;
;                 if (w < 2) { W = args.in[13 + w] + (size_t)l * D * FF; K = D; N = FF; WT = (bf16*)(WL + OFF_WGU2); rg = args.in[12] + (size_t)l * D; mode = 1 + w; }
;                 else { W = args.in[15] + (size_t)l * FF * D; K = FF; N = D; WT = (bf16*)(WL + OFF_WD2); } }
;             else if ((r -= 3 * I_GU) < I_IN) { W = args.in[6] + (size_t)l * D * INW; K = D; N = INW; WT = (bf16*)(WL + OFF_WIN); rg = args.in[5] + (size_t)l * D; mode = 3; }
;             else { r -= I_IN; W = args.in[11] + (size_t)l * D * D; K = D; N = D; WT = (bf16*)(WL + OFF_WOUT); }
;             tr_item_cu(W, K, N, WT, rg, mode, lds + nbuf * TC_BUF, r, wave, lane);
;         }
.Ldc_setup:
	v_readlane_b32 s4, v255, 28
	v_readlane_b32 s0, v255, 62
	v_readlane_b32 s1, v255, 63
	v_readlane_b32 s12, v254, 0
	v_readlane_b32 s13, v254, 1
	v_mov_b32_e32 v2, v211
	s_cmp_lg_u32 s4, 0
	s_cselect_b32 s4, 2, 0
	s_and_b32 s5, s98, 3
	s_add_i32 s4, s4, s5
	s_lshr_b32 s5, s98, 2
	s_lshl_b32 s4, s4, 2
	s_or_b32 s4, s4, s5
	s_mov_b32 s99, 1
	s_mov_b32 s101, 0
	s_cmp_eq_u32 s4, 4
	s_cselect_b32 s99, 2624, s99
	s_cselect_b32 s101, 3647, s101
	s_cmp_eq_u32 s4, 8
	s_cselect_b32 s99, 0, s99
	s_cselect_b32 s101, 127, s101
	s_cmp_eq_u32 s4, 9
	s_cselect_b32 s99, 1504, s99
	s_cselect_b32 s101, 2495, s101
	s_cmp_eq_u32 s4, 12
	s_cselect_b32 s99, 128, s99
	s_cselect_b32 s101, 383, s101
	s_cmp_eq_u32 s4, 13
	s_cselect_b32 s99, 736, s99
	s_cselect_b32 s101, 1503, s101
	s_cmp_eq_u32 s4, 16
	s_cselect_b32 s99, 384, s99
	s_cselect_b32 s101, 735, s101
	s_cmp_gt_i32 s99, s101
	s_cbranch_scc1 .Ldc_finish
	s_sub_i32 s5, s72, 0x80
	s_add_i32 s99, s99, s5
	s_cmp_gt_i32 s99, s101
	s_cbranch_scc1 .Ldc_nextpass
	s_movk_i32 s100, 0x80
	s_waitcnt lgkmcnt(0)
	s_nop 4
	s_branch .Ldc_pre
